# phase C epilogue: all 16 residual loads in flight before the first store
# baseline (speedup 1.0000x reference)
.LBB0_161:
	v_lshrrev_b32_e32 v60, 5, v78
	v_mul_u32_u24_e32 v61, 0x210, v60
	v_lshl_add_u32 v61, v79, 4, v61
	v_add_u32_e32 v62, 0x10800, v61
	v_add_u32_e32 v63, s22, v60
	v_lshlrev_b32_e32 v98, 10, v63
	v_add_u32_e32 v98, s31, v98
	v_lshl_add_u32 v98, v79, 2, v98
	v_lshlrev_b32_e32 v98, 2, v98
	v_lshlrev_b32_e32 v99, 2, v63
	v_xor_b32_e32 v182, 16, v192
	v_lshlrev_b32_e32 v182, 2, v182
	s_add_u32 s20, s94, 0x2500000
	s_addc_u32 s21, s95, 0
	s_and_b64 vcc, exec, s[44:45]
	s_cbranch_vccz .Lcepi_last
	ds_read_b128 v[12:15], v61 offset:0
	v_mov_b32_e32 v134, v98
	global_load_dwordx4 v[100:103], v134, s[92:93]
	ds_read_b128 v[16:19], v61 offset:8448
	v_add_u32_e32 v135, 0x10000, v98
	global_load_dwordx4 v[104:107], v135, s[92:93]
	ds_read_b128 v[20:23], v61 offset:16896
	v_add_u32_e32 v136, 0x20000, v98
	global_load_dwordx4 v[108:111], v136, s[92:93]
	ds_read_b128 v[24:27], v61 offset:25344
	v_add_u32_e32 v137, 0x30000, v98
	global_load_dwordx4 v[112:115], v137, s[92:93]
	ds_read_b128 v[28:31], v61 offset:33792
	v_add_u32_e32 v138, 0x40000, v98
	global_load_dwordx4 v[116:119], v138, s[92:93]
	ds_read_b128 v[32:35], v61 offset:42240
	v_add_u32_e32 v139, 0x50000, v98
	global_load_dwordx4 v[120:123], v139, s[92:93]
	ds_read_b128 v[36:39], v61 offset:50688
	v_add_u32_e32 v140, 0x60000, v98
	global_load_dwordx4 v[124:127], v140, s[92:93]
	ds_read_b128 v[40:43], v61 offset:59136
	v_add_u32_e32 v141, 0x70000, v98
	global_load_dwordx4 v[128:131], v141, s[92:93]
	ds_read_b128 v[150:153], v62 offset:0
	v_add_u32_e32 v44, 0x80000, v98
	global_load_dwordx4 v[66:69], v44, s[92:93]
	ds_read_b128 v[154:157], v62 offset:8448
	v_add_u32_e32 v45, 0x90000, v98
	global_load_dwordx4 v[70:73], v45, s[92:93]
	ds_read_b128 v[158:161], v62 offset:16896
	v_add_u32_e32 v46, 0xa0000, v98
	global_load_dwordx4 v[74:77], v46, s[92:93]
	ds_read_b128 v[162:165], v62 offset:25344
	v_add_u32_e32 v47, 0xb0000, v98
	global_load_dwordx4 v[78:81], v47, s[92:93]
	ds_read_b128 v[166:169], v62 offset:33792
	v_add_u32_e32 v48, 0xc0000, v98
	global_load_dwordx4 v[82:85], v48, s[92:93]
	ds_read_b128 v[170:173], v62 offset:42240
	v_add_u32_e32 v49, 0xd0000, v98
	global_load_dwordx4 v[86:89], v49, s[92:93]
	ds_read_b128 v[174:177], v62 offset:50688
	v_add_u32_e32 v50, 0xe0000, v98
	global_load_dwordx4 v[90:93], v50, s[92:93]
	ds_read_b128 v[178:181], v62 offset:59136
	v_add_u32_e32 v51, 0xf0000, v98
	global_load_dwordx4 v[94:97], v51, s[92:93]
	s_waitcnt vmcnt(15) lgkmcnt(15)
	v_pk_add_f32 v[100:101], v[100:101], v[12:13]
	v_pk_add_f32 v[102:103], v[102:103], v[14:15]
	global_store_dwordx4 v134, v[100:103], s[92:93]
	v_cvt_pk_bf16_f32 v12, v100, v101
	v_cvt_pk_bf16_f32 v13, v102, v103
	v_lshrrev_b32_e32 v14, 1, v134
	v_pk_mul_f32 v[100:101], v[100:101], v[100:101]
	v_pk_mul_f32 v[102:103], v[102:103], v[102:103]
	global_store_dwordx2 v14, v[12:13], s[20:21]
	v_add_f32_e32 v100, v100, v101
	v_add_f32_e32 v102, v102, v103
	v_add_f32_e32 v142, v100, v102
	s_waitcnt vmcnt(16) lgkmcnt(14)
	v_pk_add_f32 v[104:105], v[104:105], v[16:17]
	v_pk_add_f32 v[106:107], v[106:107], v[18:19]
	global_store_dwordx4 v135, v[104:107], s[92:93]
	v_cvt_pk_bf16_f32 v16, v104, v105
	v_cvt_pk_bf16_f32 v17, v106, v107
	v_lshrrev_b32_e32 v18, 1, v135
	v_pk_mul_f32 v[104:105], v[104:105], v[104:105]
	v_pk_mul_f32 v[106:107], v[106:107], v[106:107]
	global_store_dwordx2 v18, v[16:17], s[20:21]
	v_add_f32_e32 v104, v104, v105
	v_add_f32_e32 v106, v106, v107
	v_add_f32_e32 v143, v104, v106
	s_waitcnt vmcnt(17) lgkmcnt(13)
	v_pk_add_f32 v[108:109], v[108:109], v[20:21]
	v_pk_add_f32 v[110:111], v[110:111], v[22:23]
	global_store_dwordx4 v136, v[108:111], s[92:93]
	v_cvt_pk_bf16_f32 v20, v108, v109
	v_cvt_pk_bf16_f32 v21, v110, v111
	v_lshrrev_b32_e32 v22, 1, v136
	v_pk_mul_f32 v[108:109], v[108:109], v[108:109]
	v_pk_mul_f32 v[110:111], v[110:111], v[110:111]
	global_store_dwordx2 v22, v[20:21], s[20:21]
	v_add_f32_e32 v108, v108, v109
	v_add_f32_e32 v110, v110, v111
	v_add_f32_e32 v144, v108, v110
	s_waitcnt vmcnt(18) lgkmcnt(12)
	v_pk_add_f32 v[112:113], v[112:113], v[24:25]
	v_pk_add_f32 v[114:115], v[114:115], v[26:27]
	global_store_dwordx4 v137, v[112:115], s[92:93]
	v_cvt_pk_bf16_f32 v24, v112, v113
	v_cvt_pk_bf16_f32 v25, v114, v115
	v_lshrrev_b32_e32 v26, 1, v137
	v_pk_mul_f32 v[112:113], v[112:113], v[112:113]
	v_pk_mul_f32 v[114:115], v[114:115], v[114:115]
	global_store_dwordx2 v26, v[24:25], s[20:21]
	v_add_f32_e32 v112, v112, v113
	v_add_f32_e32 v114, v114, v115
	v_add_f32_e32 v145, v112, v114
	s_waitcnt vmcnt(19) lgkmcnt(11)
	v_pk_add_f32 v[116:117], v[116:117], v[28:29]
	v_pk_add_f32 v[118:119], v[118:119], v[30:31]
	global_store_dwordx4 v138, v[116:119], s[92:93]
	v_cvt_pk_bf16_f32 v28, v116, v117
	v_cvt_pk_bf16_f32 v29, v118, v119
	v_lshrrev_b32_e32 v30, 1, v138
	v_pk_mul_f32 v[116:117], v[116:117], v[116:117]
	v_pk_mul_f32 v[118:119], v[118:119], v[118:119]
	global_store_dwordx2 v30, v[28:29], s[20:21]
	v_add_f32_e32 v116, v116, v117
	v_add_f32_e32 v118, v118, v119
	v_add_f32_e32 v146, v116, v118
	s_waitcnt vmcnt(20) lgkmcnt(10)
	v_pk_add_f32 v[120:121], v[120:121], v[32:33]
	v_pk_add_f32 v[122:123], v[122:123], v[34:35]
	global_store_dwordx4 v139, v[120:123], s[92:93]
	v_cvt_pk_bf16_f32 v32, v120, v121
	v_cvt_pk_bf16_f32 v33, v122, v123
	v_lshrrev_b32_e32 v34, 1, v139
	v_pk_mul_f32 v[120:121], v[120:121], v[120:121]
	v_pk_mul_f32 v[122:123], v[122:123], v[122:123]
	global_store_dwordx2 v34, v[32:33], s[20:21]
	v_add_f32_e32 v120, v120, v121
	v_add_f32_e32 v122, v122, v123
	v_add_f32_e32 v147, v120, v122
	s_waitcnt vmcnt(21) lgkmcnt(9)
	v_pk_add_f32 v[124:125], v[124:125], v[36:37]
	v_pk_add_f32 v[126:127], v[126:127], v[38:39]
	global_store_dwordx4 v140, v[124:127], s[92:93]
	v_cvt_pk_bf16_f32 v36, v124, v125
	v_cvt_pk_bf16_f32 v37, v126, v127
	v_lshrrev_b32_e32 v38, 1, v140
	v_pk_mul_f32 v[124:125], v[124:125], v[124:125]
	v_pk_mul_f32 v[126:127], v[126:127], v[126:127]
	global_store_dwordx2 v38, v[36:37], s[20:21]
	v_add_f32_e32 v124, v124, v125
	v_add_f32_e32 v126, v126, v127
	v_add_f32_e32 v148, v124, v126
	s_waitcnt vmcnt(22) lgkmcnt(8)
	v_pk_add_f32 v[128:129], v[128:129], v[40:41]
	v_pk_add_f32 v[130:131], v[130:131], v[42:43]
	global_store_dwordx4 v141, v[128:131], s[92:93]
	v_cvt_pk_bf16_f32 v40, v128, v129
	v_cvt_pk_bf16_f32 v41, v130, v131
	v_lshrrev_b32_e32 v42, 1, v141
	v_pk_mul_f32 v[128:129], v[128:129], v[128:129]
	v_pk_mul_f32 v[130:131], v[130:131], v[130:131]
	global_store_dwordx2 v42, v[40:41], s[20:21]
	v_add_f32_e32 v128, v128, v129
	v_add_f32_e32 v130, v130, v131
	v_add_f32_e32 v149, v128, v130
	s_waitcnt vmcnt(23) lgkmcnt(7)
	v_pk_add_f32 v[66:67], v[66:67], v[150:151]
	v_pk_add_f32 v[68:69], v[68:69], v[152:153]
	global_store_dwordx4 v44, v[66:69], s[92:93]
	v_cvt_pk_bf16_f32 v150, v66, v67
	v_cvt_pk_bf16_f32 v151, v68, v69
	v_lshrrev_b32_e32 v152, 1, v44
	v_pk_mul_f32 v[66:67], v[66:67], v[66:67]
	v_pk_mul_f32 v[68:69], v[68:69], v[68:69]
	global_store_dwordx2 v152, v[150:151], s[20:21]
	v_add_f32_e32 v66, v66, v67
	v_add_f32_e32 v68, v68, v69
	v_add_f32_e32 v52, v66, v68
	s_waitcnt vmcnt(24) lgkmcnt(6)
	v_pk_add_f32 v[70:71], v[70:71], v[154:155]
	v_pk_add_f32 v[72:73], v[72:73], v[156:157]
	global_store_dwordx4 v45, v[70:73], s[92:93]
	v_cvt_pk_bf16_f32 v154, v70, v71
	v_cvt_pk_bf16_f32 v155, v72, v73
	v_lshrrev_b32_e32 v156, 1, v45
	v_pk_mul_f32 v[70:71], v[70:71], v[70:71]
	v_pk_mul_f32 v[72:73], v[72:73], v[72:73]
	global_store_dwordx2 v156, v[154:155], s[20:21]
	v_add_f32_e32 v70, v70, v71
	v_add_f32_e32 v72, v72, v73
	v_add_f32_e32 v53, v70, v72
	s_waitcnt vmcnt(25) lgkmcnt(5)
	v_pk_add_f32 v[74:75], v[74:75], v[158:159]
	v_pk_add_f32 v[76:77], v[76:77], v[160:161]
	global_store_dwordx4 v46, v[74:77], s[92:93]
	v_cvt_pk_bf16_f32 v158, v74, v75
	v_cvt_pk_bf16_f32 v159, v76, v77
	v_lshrrev_b32_e32 v160, 1, v46
	v_pk_mul_f32 v[74:75], v[74:75], v[74:75]
	v_pk_mul_f32 v[76:77], v[76:77], v[76:77]
	global_store_dwordx2 v160, v[158:159], s[20:21]
	v_add_f32_e32 v74, v74, v75
	v_add_f32_e32 v76, v76, v77
	v_add_f32_e32 v54, v74, v76
	s_waitcnt vmcnt(26) lgkmcnt(4)
	v_pk_add_f32 v[78:79], v[78:79], v[162:163]
	v_pk_add_f32 v[80:81], v[80:81], v[164:165]
	global_store_dwordx4 v47, v[78:81], s[92:93]
	v_cvt_pk_bf16_f32 v162, v78, v79
	v_cvt_pk_bf16_f32 v163, v80, v81
	v_lshrrev_b32_e32 v164, 1, v47
	v_pk_mul_f32 v[78:79], v[78:79], v[78:79]
	v_pk_mul_f32 v[80:81], v[80:81], v[80:81]
	global_store_dwordx2 v164, v[162:163], s[20:21]
	v_add_f32_e32 v78, v78, v79
	v_add_f32_e32 v80, v80, v81
	v_add_f32_e32 v55, v78, v80
	s_waitcnt vmcnt(27) lgkmcnt(3)
	v_pk_add_f32 v[82:83], v[82:83], v[166:167]
	v_pk_add_f32 v[84:85], v[84:85], v[168:169]
	global_store_dwordx4 v48, v[82:85], s[92:93]
	v_cvt_pk_bf16_f32 v166, v82, v83
	v_cvt_pk_bf16_f32 v167, v84, v85
	v_lshrrev_b32_e32 v168, 1, v48
	v_pk_mul_f32 v[82:83], v[82:83], v[82:83]
	v_pk_mul_f32 v[84:85], v[84:85], v[84:85]
	global_store_dwordx2 v168, v[166:167], s[20:21]
	v_add_f32_e32 v82, v82, v83
	v_add_f32_e32 v84, v84, v85
	v_add_f32_e32 v56, v82, v84
	s_waitcnt vmcnt(28) lgkmcnt(2)
	v_pk_add_f32 v[86:87], v[86:87], v[170:171]
	v_pk_add_f32 v[88:89], v[88:89], v[172:173]
	global_store_dwordx4 v49, v[86:89], s[92:93]
	v_cvt_pk_bf16_f32 v170, v86, v87
	v_cvt_pk_bf16_f32 v171, v88, v89
	v_lshrrev_b32_e32 v172, 1, v49
	v_pk_mul_f32 v[86:87], v[86:87], v[86:87]
	v_pk_mul_f32 v[88:89], v[88:89], v[88:89]
	global_store_dwordx2 v172, v[170:171], s[20:21]
	v_add_f32_e32 v86, v86, v87
	v_add_f32_e32 v88, v88, v89
	v_add_f32_e32 v57, v86, v88
	s_waitcnt vmcnt(29) lgkmcnt(1)
	v_pk_add_f32 v[90:91], v[90:91], v[174:175]
	v_pk_add_f32 v[92:93], v[92:93], v[176:177]
	global_store_dwordx4 v50, v[90:93], s[92:93]
	v_cvt_pk_bf16_f32 v174, v90, v91
	v_cvt_pk_bf16_f32 v175, v92, v93
	v_lshrrev_b32_e32 v176, 1, v50
	v_pk_mul_f32 v[90:91], v[90:91], v[90:91]
	v_pk_mul_f32 v[92:93], v[92:93], v[92:93]
	global_store_dwordx2 v176, v[174:175], s[20:21]
	v_add_f32_e32 v90, v90, v91
	v_add_f32_e32 v92, v92, v93
	v_add_f32_e32 v58, v90, v92
	s_waitcnt vmcnt(30) lgkmcnt(0)
	v_pk_add_f32 v[94:95], v[94:95], v[178:179]
	v_pk_add_f32 v[96:97], v[96:97], v[180:181]
	global_store_dwordx4 v51, v[94:97], s[92:93]
	v_cvt_pk_bf16_f32 v178, v94, v95
	v_cvt_pk_bf16_f32 v179, v96, v97
	v_lshrrev_b32_e32 v180, 1, v51
	v_pk_mul_f32 v[94:95], v[94:95], v[94:95]
	v_pk_mul_f32 v[96:97], v[96:97], v[96:97]
	global_store_dwordx2 v180, v[178:179], s[20:21]
	v_add_f32_e32 v94, v94, v95
	v_add_f32_e32 v96, v96, v97
	v_add_f32_e32 v59, v94, v96
	v_add_f32_dpp v142, v142, v142 quad_perm:[1,0,3,2] row_mask:0xf bank_mask:0xf bound_ctrl:1
	v_add_f32_dpp v143, v143, v143 quad_perm:[1,0,3,2] row_mask:0xf bank_mask:0xf bound_ctrl:1
	v_add_f32_dpp v144, v144, v144 quad_perm:[1,0,3,2] row_mask:0xf bank_mask:0xf bound_ctrl:1
	v_add_f32_dpp v145, v145, v145 quad_perm:[1,0,3,2] row_mask:0xf bank_mask:0xf bound_ctrl:1
	v_add_f32_dpp v146, v146, v146 quad_perm:[1,0,3,2] row_mask:0xf bank_mask:0xf bound_ctrl:1
	v_add_f32_dpp v147, v147, v147 quad_perm:[1,0,3,2] row_mask:0xf bank_mask:0xf bound_ctrl:1
	v_add_f32_dpp v148, v148, v148 quad_perm:[1,0,3,2] row_mask:0xf bank_mask:0xf bound_ctrl:1
	v_add_f32_dpp v149, v149, v149 quad_perm:[1,0,3,2] row_mask:0xf bank_mask:0xf bound_ctrl:1
	v_add_f32_dpp v52, v52, v52 quad_perm:[1,0,3,2] row_mask:0xf bank_mask:0xf bound_ctrl:1
	v_add_f32_dpp v53, v53, v53 quad_perm:[1,0,3,2] row_mask:0xf bank_mask:0xf bound_ctrl:1
	v_add_f32_dpp v54, v54, v54 quad_perm:[1,0,3,2] row_mask:0xf bank_mask:0xf bound_ctrl:1
	v_add_f32_dpp v55, v55, v55 quad_perm:[1,0,3,2] row_mask:0xf bank_mask:0xf bound_ctrl:1
	v_add_f32_dpp v56, v56, v56 quad_perm:[1,0,3,2] row_mask:0xf bank_mask:0xf bound_ctrl:1
	v_add_f32_dpp v57, v57, v57 quad_perm:[1,0,3,2] row_mask:0xf bank_mask:0xf bound_ctrl:1
	v_add_f32_dpp v58, v58, v58 quad_perm:[1,0,3,2] row_mask:0xf bank_mask:0xf bound_ctrl:1
	v_add_f32_dpp v59, v59, v59 quad_perm:[1,0,3,2] row_mask:0xf bank_mask:0xf bound_ctrl:1
	v_add_f32_dpp v142, v142, v142 quad_perm:[2,3,0,1] row_mask:0xf bank_mask:0xf bound_ctrl:1
	v_add_f32_dpp v143, v143, v143 quad_perm:[2,3,0,1] row_mask:0xf bank_mask:0xf bound_ctrl:1
	v_add_f32_dpp v144, v144, v144 quad_perm:[2,3,0,1] row_mask:0xf bank_mask:0xf bound_ctrl:1
	v_add_f32_dpp v145, v145, v145 quad_perm:[2,3,0,1] row_mask:0xf bank_mask:0xf bound_ctrl:1
	v_add_f32_dpp v146, v146, v146 quad_perm:[2,3,0,1] row_mask:0xf bank_mask:0xf bound_ctrl:1
	v_add_f32_dpp v147, v147, v147 quad_perm:[2,3,0,1] row_mask:0xf bank_mask:0xf bound_ctrl:1
	v_add_f32_dpp v148, v148, v148 quad_perm:[2,3,0,1] row_mask:0xf bank_mask:0xf bound_ctrl:1
	v_add_f32_dpp v149, v149, v149 quad_perm:[2,3,0,1] row_mask:0xf bank_mask:0xf bound_ctrl:1
	v_add_f32_dpp v52, v52, v52 quad_perm:[2,3,0,1] row_mask:0xf bank_mask:0xf bound_ctrl:1
	v_add_f32_dpp v53, v53, v53 quad_perm:[2,3,0,1] row_mask:0xf bank_mask:0xf bound_ctrl:1
	v_add_f32_dpp v54, v54, v54 quad_perm:[2,3,0,1] row_mask:0xf bank_mask:0xf bound_ctrl:1
	v_add_f32_dpp v55, v55, v55 quad_perm:[2,3,0,1] row_mask:0xf bank_mask:0xf bound_ctrl:1
	v_add_f32_dpp v56, v56, v56 quad_perm:[2,3,0,1] row_mask:0xf bank_mask:0xf bound_ctrl:1
	v_add_f32_dpp v57, v57, v57 quad_perm:[2,3,0,1] row_mask:0xf bank_mask:0xf bound_ctrl:1
	v_add_f32_dpp v58, v58, v58 quad_perm:[2,3,0,1] row_mask:0xf bank_mask:0xf bound_ctrl:1
	v_add_f32_dpp v59, v59, v59 quad_perm:[2,3,0,1] row_mask:0xf bank_mask:0xf bound_ctrl:1
	v_add_f32_dpp v142, v142, v142 row_half_mirror row_mask:0xf bank_mask:0xf bound_ctrl:1
	v_add_f32_dpp v143, v143, v143 row_half_mirror row_mask:0xf bank_mask:0xf bound_ctrl:1
	v_add_f32_dpp v144, v144, v144 row_half_mirror row_mask:0xf bank_mask:0xf bound_ctrl:1
	v_add_f32_dpp v145, v145, v145 row_half_mirror row_mask:0xf bank_mask:0xf bound_ctrl:1
	v_add_f32_dpp v146, v146, v146 row_half_mirror row_mask:0xf bank_mask:0xf bound_ctrl:1
	v_add_f32_dpp v147, v147, v147 row_half_mirror row_mask:0xf bank_mask:0xf bound_ctrl:1
	v_add_f32_dpp v148, v148, v148 row_half_mirror row_mask:0xf bank_mask:0xf bound_ctrl:1
	v_add_f32_dpp v149, v149, v149 row_half_mirror row_mask:0xf bank_mask:0xf bound_ctrl:1
	v_add_f32_dpp v52, v52, v52 row_half_mirror row_mask:0xf bank_mask:0xf bound_ctrl:1
	v_add_f32_dpp v53, v53, v53 row_half_mirror row_mask:0xf bank_mask:0xf bound_ctrl:1
	v_add_f32_dpp v54, v54, v54 row_half_mirror row_mask:0xf bank_mask:0xf bound_ctrl:1
	v_add_f32_dpp v55, v55, v55 row_half_mirror row_mask:0xf bank_mask:0xf bound_ctrl:1
	v_add_f32_dpp v56, v56, v56 row_half_mirror row_mask:0xf bank_mask:0xf bound_ctrl:1
	v_add_f32_dpp v57, v57, v57 row_half_mirror row_mask:0xf bank_mask:0xf bound_ctrl:1
	v_add_f32_dpp v58, v58, v58 row_half_mirror row_mask:0xf bank_mask:0xf bound_ctrl:1
	v_add_f32_dpp v59, v59, v59 row_half_mirror row_mask:0xf bank_mask:0xf bound_ctrl:1
	v_add_f32_dpp v142, v142, v142 row_mirror row_mask:0xf bank_mask:0xf bound_ctrl:1
	v_add_f32_dpp v143, v143, v143 row_mirror row_mask:0xf bank_mask:0xf bound_ctrl:1
	v_add_f32_dpp v144, v144, v144 row_mirror row_mask:0xf bank_mask:0xf bound_ctrl:1
	v_add_f32_dpp v145, v145, v145 row_mirror row_mask:0xf bank_mask:0xf bound_ctrl:1
	v_add_f32_dpp v146, v146, v146 row_mirror row_mask:0xf bank_mask:0xf bound_ctrl:1
	v_add_f32_dpp v147, v147, v147 row_mirror row_mask:0xf bank_mask:0xf bound_ctrl:1
	v_add_f32_dpp v148, v148, v148 row_mirror row_mask:0xf bank_mask:0xf bound_ctrl:1
	v_add_f32_dpp v149, v149, v149 row_mirror row_mask:0xf bank_mask:0xf bound_ctrl:1
	v_add_f32_dpp v52, v52, v52 row_mirror row_mask:0xf bank_mask:0xf bound_ctrl:1
	v_add_f32_dpp v53, v53, v53 row_mirror row_mask:0xf bank_mask:0xf bound_ctrl:1
	v_add_f32_dpp v54, v54, v54 row_mirror row_mask:0xf bank_mask:0xf bound_ctrl:1
	v_add_f32_dpp v55, v55, v55 row_mirror row_mask:0xf bank_mask:0xf bound_ctrl:1
	v_add_f32_dpp v56, v56, v56 row_mirror row_mask:0xf bank_mask:0xf bound_ctrl:1
	v_add_f32_dpp v57, v57, v57 row_mirror row_mask:0xf bank_mask:0xf bound_ctrl:1
	v_add_f32_dpp v58, v58, v58 row_mirror row_mask:0xf bank_mask:0xf bound_ctrl:1
	v_add_f32_dpp v59, v59, v59 row_mirror row_mask:0xf bank_mask:0xf bound_ctrl:1
	ds_bpermute_b32 v12, v182, v142
	ds_bpermute_b32 v16, v182, v143
	ds_bpermute_b32 v20, v182, v144
	ds_bpermute_b32 v24, v182, v145
	ds_bpermute_b32 v28, v182, v146
	ds_bpermute_b32 v32, v182, v147
	ds_bpermute_b32 v36, v182, v148
	ds_bpermute_b32 v40, v182, v149
	ds_bpermute_b32 v150, v182, v52
	ds_bpermute_b32 v154, v182, v53
	ds_bpermute_b32 v158, v182, v54
	ds_bpermute_b32 v162, v182, v55
	ds_bpermute_b32 v166, v182, v56
	ds_bpermute_b32 v170, v182, v57
	ds_bpermute_b32 v174, v182, v58
	ds_bpermute_b32 v178, v182, v59
	s_waitcnt lgkmcnt(0)
	v_add_f32_e32 v142, v142, v12
	v_add_f32_e32 v143, v143, v16
	v_add_f32_e32 v144, v144, v20
	v_add_f32_e32 v145, v145, v24
	v_add_f32_e32 v146, v146, v28
	v_add_f32_e32 v147, v147, v32
	v_add_f32_e32 v148, v148, v36
	v_add_f32_e32 v149, v149, v40
	v_add_f32_e32 v52, v52, v150
	v_add_f32_e32 v53, v53, v154
	v_add_f32_e32 v54, v54, v158
	v_add_f32_e32 v55, v55, v162
	v_add_f32_e32 v56, v56, v166
	v_add_f32_e32 v57, v57, v170
	v_add_f32_e32 v58, v58, v174
	v_add_f32_e32 v59, v59, v178
	v_add_u32_e32 v13, 0x0, v99
	v_add_u32_e32 v17, 0x40, v99
	v_add_u32_e32 v21, 0x80, v99
	v_add_u32_e32 v25, 0xc0, v99
	v_add_u32_e32 v29, 0x100, v99
	v_add_u32_e32 v33, 0x140, v99
	v_add_u32_e32 v37, 0x180, v99
	v_add_u32_e32 v41, 0x1c0, v99
	v_add_u32_e32 v151, 0x200, v99
	v_add_u32_e32 v155, 0x240, v99
	v_add_u32_e32 v159, 0x280, v99
	v_add_u32_e32 v163, 0x2c0, v99
	v_add_u32_e32 v167, 0x300, v99
	v_add_u32_e32 v171, 0x340, v99
	v_add_u32_e32 v175, 0x380, v99
	v_add_u32_e32 v179, 0x3c0, v99
	s_mov_b64 exec, s[0:1]
	global_atomic_add_f32 v13, v142, s[50:51]
	global_atomic_add_f32 v17, v143, s[50:51]
	global_atomic_add_f32 v21, v144, s[50:51]
	global_atomic_add_f32 v25, v145, s[50:51]
	global_atomic_add_f32 v29, v146, s[50:51]
	global_atomic_add_f32 v33, v147, s[50:51]
	global_atomic_add_f32 v37, v148, s[50:51]
	global_atomic_add_f32 v41, v149, s[50:51]
	global_atomic_add_f32 v151, v52, s[50:51]
	global_atomic_add_f32 v155, v53, s[50:51]
	global_atomic_add_f32 v159, v54, s[50:51]
	global_atomic_add_f32 v163, v55, s[50:51]
	global_atomic_add_f32 v167, v56, s[50:51]
	global_atomic_add_f32 v171, v57, s[50:51]
	global_atomic_add_f32 v175, v58, s[50:51]
	global_atomic_add_f32 v179, v59, s[50:51]
	s_mov_b64 exec, -1
	s_branch .LBB0_158
.Lcepi_last:
	ds_read_b128 v[12:15], v61 offset:0
	v_mov_b32_e32 v134, v98
	global_load_dwordx4 v[100:103], v134, s[92:93]
	ds_read_b128 v[16:19], v61 offset:8448
	v_add_u32_e32 v135, 0x10000, v98
	global_load_dwordx4 v[104:107], v135, s[92:93]
	ds_read_b128 v[20:23], v61 offset:16896
	v_add_u32_e32 v136, 0x20000, v98
	global_load_dwordx4 v[108:111], v136, s[92:93]
	ds_read_b128 v[24:27], v61 offset:25344
	v_add_u32_e32 v137, 0x30000, v98
	global_load_dwordx4 v[112:115], v137, s[92:93]
	ds_read_b128 v[28:31], v61 offset:33792
	v_add_u32_e32 v138, 0x40000, v98
	global_load_dwordx4 v[116:119], v138, s[92:93]
	ds_read_b128 v[32:35], v61 offset:42240
	v_add_u32_e32 v139, 0x50000, v98
	global_load_dwordx4 v[120:123], v139, s[92:93]
	ds_read_b128 v[36:39], v61 offset:50688
	v_add_u32_e32 v140, 0x60000, v98
	global_load_dwordx4 v[124:127], v140, s[92:93]
	ds_read_b128 v[40:43], v61 offset:59136
	v_add_u32_e32 v141, 0x70000, v98
	global_load_dwordx4 v[128:131], v141, s[92:93]
	ds_read_b128 v[150:153], v62 offset:0
	v_add_u32_e32 v44, 0x80000, v98
	global_load_dwordx4 v[66:69], v44, s[92:93]
	ds_read_b128 v[154:157], v62 offset:8448
	v_add_u32_e32 v45, 0x90000, v98
	global_load_dwordx4 v[70:73], v45, s[92:93]
	ds_read_b128 v[158:161], v62 offset:16896
	v_add_u32_e32 v46, 0xa0000, v98
	global_load_dwordx4 v[74:77], v46, s[92:93]
	ds_read_b128 v[162:165], v62 offset:25344
	v_add_u32_e32 v47, 0xb0000, v98
	global_load_dwordx4 v[78:81], v47, s[92:93]
	ds_read_b128 v[166:169], v62 offset:33792
	v_add_u32_e32 v48, 0xc0000, v98
	global_load_dwordx4 v[82:85], v48, s[92:93]
	ds_read_b128 v[170:173], v62 offset:42240
	v_add_u32_e32 v49, 0xd0000, v98
	global_load_dwordx4 v[86:89], v49, s[92:93]
	ds_read_b128 v[174:177], v62 offset:50688
	v_add_u32_e32 v50, 0xe0000, v98
	global_load_dwordx4 v[90:93], v50, s[92:93]
	ds_read_b128 v[178:181], v62 offset:59136
	v_add_u32_e32 v51, 0xf0000, v98
	global_load_dwordx4 v[94:97], v51, s[92:93]
	s_waitcnt vmcnt(15) lgkmcnt(15)
	v_pk_add_f32 v[100:101], v[100:101], v[12:13]
	v_pk_add_f32 v[102:103], v[102:103], v[14:15]
	global_store_dwordx4 v134, v[100:103], s[92:93]
	s_waitcnt vmcnt(15) lgkmcnt(14)
	v_pk_add_f32 v[104:105], v[104:105], v[16:17]
	v_pk_add_f32 v[106:107], v[106:107], v[18:19]
	global_store_dwordx4 v135, v[104:107], s[92:93]
	s_waitcnt vmcnt(15) lgkmcnt(13)
	v_pk_add_f32 v[108:109], v[108:109], v[20:21]
	v_pk_add_f32 v[110:111], v[110:111], v[22:23]
	global_store_dwordx4 v136, v[108:111], s[92:93]
	s_waitcnt vmcnt(15) lgkmcnt(12)
	v_pk_add_f32 v[112:113], v[112:113], v[24:25]
	v_pk_add_f32 v[114:115], v[114:115], v[26:27]
	global_store_dwordx4 v137, v[112:115], s[92:93]
	s_waitcnt vmcnt(15) lgkmcnt(11)
	v_pk_add_f32 v[116:117], v[116:117], v[28:29]
	v_pk_add_f32 v[118:119], v[118:119], v[30:31]
	global_store_dwordx4 v138, v[116:119], s[92:93]
	s_waitcnt vmcnt(15) lgkmcnt(10)
	v_pk_add_f32 v[120:121], v[120:121], v[32:33]
	v_pk_add_f32 v[122:123], v[122:123], v[34:35]
	global_store_dwordx4 v139, v[120:123], s[92:93]
	s_waitcnt vmcnt(15) lgkmcnt(9)
	v_pk_add_f32 v[124:125], v[124:125], v[36:37]
	v_pk_add_f32 v[126:127], v[126:127], v[38:39]
	global_store_dwordx4 v140, v[124:127], s[92:93]
	s_waitcnt vmcnt(15) lgkmcnt(8)
	v_pk_add_f32 v[128:129], v[128:129], v[40:41]
	v_pk_add_f32 v[130:131], v[130:131], v[42:43]
	global_store_dwordx4 v141, v[128:131], s[92:93]
	s_waitcnt vmcnt(15) lgkmcnt(7)
	v_pk_add_f32 v[66:67], v[66:67], v[150:151]
	v_pk_add_f32 v[68:69], v[68:69], v[152:153]
	global_store_dwordx4 v44, v[66:69], s[92:93]
	s_waitcnt vmcnt(15) lgkmcnt(6)
	v_pk_add_f32 v[70:71], v[70:71], v[154:155]
	v_pk_add_f32 v[72:73], v[72:73], v[156:157]
	global_store_dwordx4 v45, v[70:73], s[92:93]
	s_waitcnt vmcnt(15) lgkmcnt(5)
	v_pk_add_f32 v[74:75], v[74:75], v[158:159]
	v_pk_add_f32 v[76:77], v[76:77], v[160:161]
	global_store_dwordx4 v46, v[74:77], s[92:93]
	s_waitcnt vmcnt(15) lgkmcnt(4)
	v_pk_add_f32 v[78:79], v[78:79], v[162:163]
	v_pk_add_f32 v[80:81], v[80:81], v[164:165]
	global_store_dwordx4 v47, v[78:81], s[92:93]
	s_waitcnt vmcnt(15) lgkmcnt(3)
	v_pk_add_f32 v[82:83], v[82:83], v[166:167]
	v_pk_add_f32 v[84:85], v[84:85], v[168:169]
	global_store_dwordx4 v48, v[82:85], s[92:93]
	s_waitcnt vmcnt(15) lgkmcnt(2)
	v_pk_add_f32 v[86:87], v[86:87], v[170:171]
	v_pk_add_f32 v[88:89], v[88:89], v[172:173]
	global_store_dwordx4 v49, v[86:89], s[92:93]
	s_waitcnt vmcnt(15) lgkmcnt(1)
	v_pk_add_f32 v[90:91], v[90:91], v[174:175]
	v_pk_add_f32 v[92:93], v[92:93], v[176:177]
	global_store_dwordx4 v50, v[90:93], s[92:93]
	s_waitcnt vmcnt(15) lgkmcnt(0)
	v_pk_add_f32 v[94:95], v[94:95], v[178:179]
	v_pk_add_f32 v[96:97], v[96:97], v[180:181]
	global_store_dwordx4 v51, v[94:97], s[92:93]
	s_branch .LBB0_158

.LBB0_244:
	v_lshrrev_b32_e32 v60, 5, v74
	v_mul_u32_u24_e32 v61, 0x210, v60
	v_lshl_add_u32 v61, v75, 4, v61
	v_add_u32_e32 v62, 0x10800, v61
	v_add_u32_e32 v63, 0x4000, v60
	v_lshlrev_b32_e32 v98, 10, v63
	v_add_u32_e32 v98, s53, v98
	v_lshl_add_u32 v98, v75, 2, v98
	v_lshlrev_b32_e32 v98, 2, v98
	v_lshlrev_b32_e32 v99, 2, v63
	v_xor_b32_e32 v182, 16, v192
	v_lshlrev_b32_e32 v182, 2, v182
	s_add_u32 s20, s94, 0x2500000
	s_addc_u32 s21, s95, 0
	s_and_b64 vcc, exec, s[44:45]
	s_cbranch_vccz .Lcepi_last_b3
	ds_read_b128 v[12:15], v61 offset:0
	v_mov_b32_e32 v134, v98
	global_load_dwordx4 v[100:103], v134, s[92:93]
	ds_read_b128 v[16:19], v61 offset:8448
	v_add_u32_e32 v135, 0x10000, v98
	global_load_dwordx4 v[104:107], v135, s[92:93]
	ds_read_b128 v[20:23], v61 offset:16896
	v_add_u32_e32 v136, 0x20000, v98
	global_load_dwordx4 v[108:111], v136, s[92:93]
	ds_read_b128 v[24:27], v61 offset:25344
	v_add_u32_e32 v137, 0x30000, v98
	global_load_dwordx4 v[112:115], v137, s[92:93]
	ds_read_b128 v[28:31], v61 offset:33792
	v_add_u32_e32 v138, 0x40000, v98
	global_load_dwordx4 v[116:119], v138, s[92:93]
	ds_read_b128 v[32:35], v61 offset:42240
	v_add_u32_e32 v139, 0x50000, v98
	global_load_dwordx4 v[120:123], v139, s[92:93]
	ds_read_b128 v[36:39], v61 offset:50688
	v_add_u32_e32 v140, 0x60000, v98
	global_load_dwordx4 v[124:127], v140, s[92:93]
	ds_read_b128 v[40:43], v61 offset:59136
	v_add_u32_e32 v141, 0x70000, v98
	global_load_dwordx4 v[128:131], v141, s[92:93]
	s_waitcnt vmcnt(7) lgkmcnt(7)
	v_pk_add_f32 v[100:101], v[100:101], v[12:13]
	v_pk_add_f32 v[102:103], v[102:103], v[14:15]
	global_store_dwordx4 v134, v[100:103], s[92:93]
	v_cvt_pk_bf16_f32 v12, v100, v101
	v_cvt_pk_bf16_f32 v13, v102, v103
	v_lshrrev_b32_e32 v14, 1, v134
	v_pk_mul_f32 v[100:101], v[100:101], v[100:101]
	v_pk_mul_f32 v[102:103], v[102:103], v[102:103]
	global_store_dwordx2 v14, v[12:13], s[20:21]
	v_add_f32_e32 v100, v100, v101
	v_add_f32_e32 v102, v102, v103
	v_add_f32_e32 v142, v100, v102
	s_waitcnt vmcnt(8) lgkmcnt(6)
	v_pk_add_f32 v[104:105], v[104:105], v[16:17]
	v_pk_add_f32 v[106:107], v[106:107], v[18:19]
	global_store_dwordx4 v135, v[104:107], s[92:93]
	v_cvt_pk_bf16_f32 v16, v104, v105
	v_cvt_pk_bf16_f32 v17, v106, v107
	v_lshrrev_b32_e32 v18, 1, v135
	v_pk_mul_f32 v[104:105], v[104:105], v[104:105]
	v_pk_mul_f32 v[106:107], v[106:107], v[106:107]
	global_store_dwordx2 v18, v[16:17], s[20:21]
	v_add_f32_e32 v104, v104, v105
	v_add_f32_e32 v106, v106, v107
	v_add_f32_e32 v143, v104, v106
	s_waitcnt vmcnt(9) lgkmcnt(5)
	v_pk_add_f32 v[108:109], v[108:109], v[20:21]
	v_pk_add_f32 v[110:111], v[110:111], v[22:23]
	global_store_dwordx4 v136, v[108:111], s[92:93]
	v_cvt_pk_bf16_f32 v20, v108, v109
	v_cvt_pk_bf16_f32 v21, v110, v111
	v_lshrrev_b32_e32 v22, 1, v136
	v_pk_mul_f32 v[108:109], v[108:109], v[108:109]
	v_pk_mul_f32 v[110:111], v[110:111], v[110:111]
	global_store_dwordx2 v22, v[20:21], s[20:21]
	v_add_f32_e32 v108, v108, v109
	v_add_f32_e32 v110, v110, v111
	v_add_f32_e32 v144, v108, v110
	s_waitcnt vmcnt(10) lgkmcnt(4)
	v_pk_add_f32 v[112:113], v[112:113], v[24:25]
	v_pk_add_f32 v[114:115], v[114:115], v[26:27]
	global_store_dwordx4 v137, v[112:115], s[92:93]
	v_cvt_pk_bf16_f32 v24, v112, v113
	v_cvt_pk_bf16_f32 v25, v114, v115
	v_lshrrev_b32_e32 v26, 1, v137
	v_pk_mul_f32 v[112:113], v[112:113], v[112:113]
	v_pk_mul_f32 v[114:115], v[114:115], v[114:115]
	global_store_dwordx2 v26, v[24:25], s[20:21]
	v_add_f32_e32 v112, v112, v113
	v_add_f32_e32 v114, v114, v115
	v_add_f32_e32 v145, v112, v114
	s_waitcnt vmcnt(11) lgkmcnt(3)
	v_pk_add_f32 v[116:117], v[116:117], v[28:29]
	v_pk_add_f32 v[118:119], v[118:119], v[30:31]
	global_store_dwordx4 v138, v[116:119], s[92:93]
	v_cvt_pk_bf16_f32 v28, v116, v117
	v_cvt_pk_bf16_f32 v29, v118, v119
	v_lshrrev_b32_e32 v30, 1, v138
	v_pk_mul_f32 v[116:117], v[116:117], v[116:117]
	v_pk_mul_f32 v[118:119], v[118:119], v[118:119]
	global_store_dwordx2 v30, v[28:29], s[20:21]
	v_add_f32_e32 v116, v116, v117
	v_add_f32_e32 v118, v118, v119
	v_add_f32_e32 v146, v116, v118
	s_waitcnt vmcnt(12) lgkmcnt(2)
	v_pk_add_f32 v[120:121], v[120:121], v[32:33]
	v_pk_add_f32 v[122:123], v[122:123], v[34:35]
	global_store_dwordx4 v139, v[120:123], s[92:93]
	v_cvt_pk_bf16_f32 v32, v120, v121
	v_cvt_pk_bf16_f32 v33, v122, v123
	v_lshrrev_b32_e32 v34, 1, v139
	v_pk_mul_f32 v[120:121], v[120:121], v[120:121]
	v_pk_mul_f32 v[122:123], v[122:123], v[122:123]
	global_store_dwordx2 v34, v[32:33], s[20:21]
	v_add_f32_e32 v120, v120, v121
	v_add_f32_e32 v122, v122, v123
	v_add_f32_e32 v147, v120, v122
	s_waitcnt vmcnt(13) lgkmcnt(1)
	v_pk_add_f32 v[124:125], v[124:125], v[36:37]
	v_pk_add_f32 v[126:127], v[126:127], v[38:39]
	global_store_dwordx4 v140, v[124:127], s[92:93]
	v_cvt_pk_bf16_f32 v36, v124, v125
	v_cvt_pk_bf16_f32 v37, v126, v127
	v_lshrrev_b32_e32 v38, 1, v140
	v_pk_mul_f32 v[124:125], v[124:125], v[124:125]
	v_pk_mul_f32 v[126:127], v[126:127], v[126:127]
	global_store_dwordx2 v38, v[36:37], s[20:21]
	v_add_f32_e32 v124, v124, v125
	v_add_f32_e32 v126, v126, v127
	v_add_f32_e32 v148, v124, v126
	s_waitcnt vmcnt(14) lgkmcnt(0)
	v_pk_add_f32 v[128:129], v[128:129], v[40:41]
	v_pk_add_f32 v[130:131], v[130:131], v[42:43]
	global_store_dwordx4 v141, v[128:131], s[92:93]
	v_cvt_pk_bf16_f32 v40, v128, v129
	v_cvt_pk_bf16_f32 v41, v130, v131
	v_lshrrev_b32_e32 v42, 1, v141
	v_pk_mul_f32 v[128:129], v[128:129], v[128:129]
	v_pk_mul_f32 v[130:131], v[130:131], v[130:131]
	global_store_dwordx2 v42, v[40:41], s[20:21]
	v_add_f32_e32 v128, v128, v129
	v_add_f32_e32 v130, v130, v131
	v_add_f32_e32 v149, v128, v130
	v_add_f32_dpp v142, v142, v142 quad_perm:[1,0,3,2] row_mask:0xf bank_mask:0xf bound_ctrl:1
	v_add_f32_dpp v143, v143, v143 quad_perm:[1,0,3,2] row_mask:0xf bank_mask:0xf bound_ctrl:1
	v_add_f32_dpp v144, v144, v144 quad_perm:[1,0,3,2] row_mask:0xf bank_mask:0xf bound_ctrl:1
	v_add_f32_dpp v145, v145, v145 quad_perm:[1,0,3,2] row_mask:0xf bank_mask:0xf bound_ctrl:1
	v_add_f32_dpp v146, v146, v146 quad_perm:[1,0,3,2] row_mask:0xf bank_mask:0xf bound_ctrl:1
	v_add_f32_dpp v147, v147, v147 quad_perm:[1,0,3,2] row_mask:0xf bank_mask:0xf bound_ctrl:1
	v_add_f32_dpp v148, v148, v148 quad_perm:[1,0,3,2] row_mask:0xf bank_mask:0xf bound_ctrl:1
	v_add_f32_dpp v149, v149, v149 quad_perm:[1,0,3,2] row_mask:0xf bank_mask:0xf bound_ctrl:1
	v_add_f32_dpp v142, v142, v142 quad_perm:[2,3,0,1] row_mask:0xf bank_mask:0xf bound_ctrl:1
	v_add_f32_dpp v143, v143, v143 quad_perm:[2,3,0,1] row_mask:0xf bank_mask:0xf bound_ctrl:1
	v_add_f32_dpp v144, v144, v144 quad_perm:[2,3,0,1] row_mask:0xf bank_mask:0xf bound_ctrl:1
	v_add_f32_dpp v145, v145, v145 quad_perm:[2,3,0,1] row_mask:0xf bank_mask:0xf bound_ctrl:1
	v_add_f32_dpp v146, v146, v146 quad_perm:[2,3,0,1] row_mask:0xf bank_mask:0xf bound_ctrl:1
	v_add_f32_dpp v147, v147, v147 quad_perm:[2,3,0,1] row_mask:0xf bank_mask:0xf bound_ctrl:1
	v_add_f32_dpp v148, v148, v148 quad_perm:[2,3,0,1] row_mask:0xf bank_mask:0xf bound_ctrl:1
	v_add_f32_dpp v149, v149, v149 quad_perm:[2,3,0,1] row_mask:0xf bank_mask:0xf bound_ctrl:1
	v_add_f32_dpp v142, v142, v142 row_half_mirror row_mask:0xf bank_mask:0xf bound_ctrl:1
	v_add_f32_dpp v143, v143, v143 row_half_mirror row_mask:0xf bank_mask:0xf bound_ctrl:1
	v_add_f32_dpp v144, v144, v144 row_half_mirror row_mask:0xf bank_mask:0xf bound_ctrl:1
	v_add_f32_dpp v145, v145, v145 row_half_mirror row_mask:0xf bank_mask:0xf bound_ctrl:1
	v_add_f32_dpp v146, v146, v146 row_half_mirror row_mask:0xf bank_mask:0xf bound_ctrl:1
	v_add_f32_dpp v147, v147, v147 row_half_mirror row_mask:0xf bank_mask:0xf bound_ctrl:1
	v_add_f32_dpp v148, v148, v148 row_half_mirror row_mask:0xf bank_mask:0xf bound_ctrl:1
	v_add_f32_dpp v149, v149, v149 row_half_mirror row_mask:0xf bank_mask:0xf bound_ctrl:1
	v_add_f32_dpp v142, v142, v142 row_mirror row_mask:0xf bank_mask:0xf bound_ctrl:1
	v_add_f32_dpp v143, v143, v143 row_mirror row_mask:0xf bank_mask:0xf bound_ctrl:1
	v_add_f32_dpp v144, v144, v144 row_mirror row_mask:0xf bank_mask:0xf bound_ctrl:1
	v_add_f32_dpp v145, v145, v145 row_mirror row_mask:0xf bank_mask:0xf bound_ctrl:1
	v_add_f32_dpp v146, v146, v146 row_mirror row_mask:0xf bank_mask:0xf bound_ctrl:1
	v_add_f32_dpp v147, v147, v147 row_mirror row_mask:0xf bank_mask:0xf bound_ctrl:1
	v_add_f32_dpp v148, v148, v148 row_mirror row_mask:0xf bank_mask:0xf bound_ctrl:1
	v_add_f32_dpp v149, v149, v149 row_mirror row_mask:0xf bank_mask:0xf bound_ctrl:1
	ds_bpermute_b32 v12, v182, v142
	ds_bpermute_b32 v16, v182, v143
	ds_bpermute_b32 v20, v182, v144
	ds_bpermute_b32 v24, v182, v145
	ds_bpermute_b32 v28, v182, v146
	ds_bpermute_b32 v32, v182, v147
	ds_bpermute_b32 v36, v182, v148
	ds_bpermute_b32 v40, v182, v149
	s_waitcnt lgkmcnt(0)
	v_add_f32_e32 v142, v142, v12
	v_add_f32_e32 v143, v143, v16
	v_add_f32_e32 v144, v144, v20
	v_add_f32_e32 v145, v145, v24
	v_add_f32_e32 v146, v146, v28
	v_add_f32_e32 v147, v147, v32
	v_add_f32_e32 v148, v148, v36
	v_add_f32_e32 v149, v149, v40
	v_add_u32_e32 v13, 0x0, v99
	v_add_u32_e32 v17, 0x40, v99
	v_add_u32_e32 v21, 0x80, v99
	v_add_u32_e32 v25, 0xc0, v99
	v_add_u32_e32 v29, 0x100, v99
	v_add_u32_e32 v33, 0x140, v99
	v_add_u32_e32 v37, 0x180, v99
	v_add_u32_e32 v41, 0x1c0, v99
	s_mov_b64 exec, s[0:1]
	global_atomic_add_f32 v13, v142, s[50:51]
	global_atomic_add_f32 v17, v143, s[50:51]
	global_atomic_add_f32 v21, v144, s[50:51]
	global_atomic_add_f32 v25, v145, s[50:51]
	global_atomic_add_f32 v29, v146, s[50:51]
	global_atomic_add_f32 v33, v147, s[50:51]
	global_atomic_add_f32 v37, v148, s[50:51]
	global_atomic_add_f32 v41, v149, s[50:51]
	s_mov_b64 exec, -1
	s_branch .LBB0_280
.Lcepi_last_b3:
	ds_read_b128 v[12:15], v61 offset:0
	v_mov_b32_e32 v134, v98
	global_load_dwordx4 v[100:103], v134, s[92:93]
	ds_read_b128 v[16:19], v61 offset:8448
	v_add_u32_e32 v135, 0x10000, v98
	global_load_dwordx4 v[104:107], v135, s[92:93]
	ds_read_b128 v[20:23], v61 offset:16896
	v_add_u32_e32 v136, 0x20000, v98
	global_load_dwordx4 v[108:111], v136, s[92:93]
	ds_read_b128 v[24:27], v61 offset:25344
	v_add_u32_e32 v137, 0x30000, v98
	global_load_dwordx4 v[112:115], v137, s[92:93]
	ds_read_b128 v[28:31], v61 offset:33792
	v_add_u32_e32 v138, 0x40000, v98
	global_load_dwordx4 v[116:119], v138, s[92:93]
	ds_read_b128 v[32:35], v61 offset:42240
	v_add_u32_e32 v139, 0x50000, v98
	global_load_dwordx4 v[120:123], v139, s[92:93]
	ds_read_b128 v[36:39], v61 offset:50688
	v_add_u32_e32 v140, 0x60000, v98
	global_load_dwordx4 v[124:127], v140, s[92:93]
	ds_read_b128 v[40:43], v61 offset:59136
	v_add_u32_e32 v141, 0x70000, v98
	global_load_dwordx4 v[128:131], v141, s[92:93]
	s_waitcnt vmcnt(7) lgkmcnt(7)
	v_pk_add_f32 v[100:101], v[100:101], v[12:13]
	v_pk_add_f32 v[102:103], v[102:103], v[14:15]
	global_store_dwordx4 v134, v[100:103], s[92:93]
	s_waitcnt vmcnt(7) lgkmcnt(6)
	v_pk_add_f32 v[104:105], v[104:105], v[16:17]
	v_pk_add_f32 v[106:107], v[106:107], v[18:19]
	global_store_dwordx4 v135, v[104:107], s[92:93]
	s_waitcnt vmcnt(7) lgkmcnt(5)
	v_pk_add_f32 v[108:109], v[108:109], v[20:21]
	v_pk_add_f32 v[110:111], v[110:111], v[22:23]
	global_store_dwordx4 v136, v[108:111], s[92:93]
	s_waitcnt vmcnt(7) lgkmcnt(4)
	v_pk_add_f32 v[112:113], v[112:113], v[24:25]
	v_pk_add_f32 v[114:115], v[114:115], v[26:27]
	global_store_dwordx4 v137, v[112:115], s[92:93]
	s_waitcnt vmcnt(7) lgkmcnt(3)
	v_pk_add_f32 v[116:117], v[116:117], v[28:29]
	v_pk_add_f32 v[118:119], v[118:119], v[30:31]
	global_store_dwordx4 v138, v[116:119], s[92:93]
	s_waitcnt vmcnt(7) lgkmcnt(2)
	v_pk_add_f32 v[120:121], v[120:121], v[32:33]
	v_pk_add_f32 v[122:123], v[122:123], v[34:35]
	global_store_dwordx4 v139, v[120:123], s[92:93]
	s_waitcnt vmcnt(7) lgkmcnt(1)
	v_pk_add_f32 v[124:125], v[124:125], v[36:37]
	v_pk_add_f32 v[126:127], v[126:127], v[38:39]
	global_store_dwordx4 v140, v[124:127], s[92:93]
	s_waitcnt vmcnt(7) lgkmcnt(0)
	v_pk_add_f32 v[128:129], v[128:129], v[40:41]
	v_pk_add_f32 v[130:131], v[130:131], v[42:43]
	global_store_dwordx4 v141, v[128:131], s[92:93]
	s_branch .LBB0_280
